# attention unit epilogue: closing barrier no longer waits for the output stores to drain (next unit's loads overlap them)
# speedup vs baseline: 1.0016x; 1.0016x over previous
; __device__ __forceinline__ unsigned cvt_pk_bf16(float lo, float hi) { unsigned r; asm volatile("v_cvt_pk_bf16_f32 %0, %1, %2" : "=v"(r) : "v"(lo), "v"(hi)); return r; }
; __device__ __forceinline__ int crow(int r, int hi) { return (r & 3) + 8 * (r >> 2) + 4 * hi; }
; __device__ __forceinline__ void attn_unit(const bf16_t* __restrict__ Qb, const bf16_t* __restrict__ Kn, const bf16_t* __restrict__ Vh, const bf16_t* __restrict__ Kr,
;                                           bf16_t* __restrict__ Ob, int seq, char* lds, int wv_) { LAUNDER_IDS;
;     ...
;     if (hi == 0) li_l[r32] = l_reg; asm volatile("s_waitcnt lgkmcnt(0)" ::: "memory");
;     float rli[16];
; #pragma unroll
;     for (int r = 0; r < 16; ++r) rli[r] = __builtin_amdgcn_rcpf(li_l[crow(r, hi)]);
;     bf16_t* Ow = Ob + (long)(wid * QBLK) * LDO;
; #pragma unroll
;     for (int r = 0; r < 16; ++r) { const int orow = crow(r, hi);
; #pragma unroll
;         for (int d0 = 0; d0 < 4; ++d0) Ow[(long)orow * LDO + d0 * 32 + r32] = (bf16_t)(cvt_pk_bf16(o[d0][r] * rli[r], 0.f) & 0xffffu); }
.LBB0_213:
	s_or_b64 exec, exec, s[0:1]
	s_waitcnt lgkmcnt(0)
	v_add_u32_e32 v72, s5, v160
	s_lshl_b32 s0, s4, 12
	v_readlane_b32 s1, v251, 52
	ds_read_b128 v[64:67], v72
	ds_read_b128 v[68:71], v72 offset:32
	s_add_u32 s4, s1, s0
	v_readlane_b32 s0, v251, 53
	s_addc_u32 s6, s0, 0
	s_lshl_b32 s0, s3, 7
	s_ashr_i32 s1, s0, 31
	s_lshl_b64 s[0:1], s[0:1], 1
	s_add_u32 s3, s4, s0
	s_waitcnt lgkmcnt(0)
	v_rcp_f32_e32 v73, v64
	v_rcp_f32_e32 v74, v65
	v_rcp_f32_e32 v75, v66
	v_rcp_f32_e32 v76, v67
	ds_read_b128 v[64:67], v72 offset:64
	s_addc_u32 s4, s6, s1
	s_ashr_i32 s13, s12, 31
	s_lshl_b64 s[0:1], s[12:13], 12
	s_add_u32 s0, s3, s0
	s_addc_u32 s1, s4, s1
	v_lshlrev_b32_e32 v160, 1, v183
	v_rcp_f32_e32 v77, v68
	v_rcp_f32_e32 v78, v69
	v_rcp_f32_e32 v79, v70
	v_rcp_f32_e32 v80, v71
	ds_read_b128 v[68:71], v72 offset:96
	s_waitcnt lgkmcnt(0)
	v_rcp_f32_e32 v72, v64
	v_rcp_f32_e32 v81, v65
	v_rcp_f32_e32 v82, v66
	v_rcp_f32_e32 v83, v67
	v_lshlrev_b32_e32 v64, 14, v185
	v_lshl_add_u64 v[66:67], s[0:1], 0, v[160:161]
	v_mov_b32_e32 v65, v161
	v_mul_f32_e32 v0, v0, v73
	v_lshl_add_u64 v[64:65], v[66:67], 0, v[64:65]
	v_cvt_pk_bf16_f32 v0, v0, v161
	global_store_short v[64:65], v0, off
	v_mul_f32_e32 v0, v48, v73
	v_cvt_pk_bf16_f32 v0, v0, v161
	global_store_short v[64:65], v0, off offset:64
	v_mul_f32_e32 v0, v32, v73
	v_cvt_pk_bf16_f32 v0, v0, v161
	global_store_short v[64:65], v0, off offset:128
	v_mul_f32_e32 v0, v16, v73
	v_cvt_pk_bf16_f32 v0, v0, v161
	global_store_short v[64:65], v0, off offset:192
	v_mul_f32_e32 v0, v1, v74
	s_movk_i32 s0, 0x1000
	v_cvt_pk_bf16_f32 v16, v0, v161
	v_add_co_u32_e32 v0, vcc, s0, v64
	s_movk_i32 s0, 0x2000
	s_nop 0
	v_addc_co_u32_e32 v1, vcc, 0, v65, vcc
	v_add_co_u32_e32 v66, vcc, s0, v64
	s_movk_i32 s0, 0x3000
	s_nop 0
	v_addc_co_u32_e32 v67, vcc, 0, v65, vcc
	global_store_short v[66:67], v16, off offset:-4096
	v_mul_f32_e32 v16, v49, v74
	v_cvt_pk_bf16_f32 v16, v16, v161
	global_store_short v[0:1], v16, off offset:64
	v_mul_f32_e32 v16, v33, v74
	v_cvt_pk_bf16_f32 v16, v16, v161
	global_store_short v[0:1], v16, off offset:128
	v_mul_f32_e32 v16, v17, v74
	v_cvt_pk_bf16_f32 v16, v16, v161
	global_store_short v[0:1], v16, off offset:192
	v_mul_f32_e32 v0, v2, v75
	v_cvt_pk_bf16_f32 v0, v0, v161
	global_store_short v[66:67], v0, off
	v_mul_f32_e32 v0, v50, v75
	v_cvt_pk_bf16_f32 v0, v0, v161
	global_store_short v[66:67], v0, off offset:64
	v_mul_f32_e32 v0, v34, v75
	v_cvt_pk_bf16_f32 v0, v0, v161
	global_store_short v[66:67], v0, off offset:128
	v_mul_f32_e32 v0, v18, v75
	v_cvt_pk_bf16_f32 v0, v0, v161
	global_store_short v[66:67], v0, off offset:192
	v_mul_f32_e32 v0, v3, v76
	v_cvt_pk_bf16_f32 v2, v0, v161
	v_add_co_u32_e32 v0, vcc, s0, v64
	s_mov_b32 s0, 0x8000
	s_nop 0
	v_addc_co_u32_e32 v1, vcc, 0, v65, vcc
	global_store_short v[0:1], v2, off
	v_mul_f32_e32 v2, v51, v76
	v_cvt_pk_bf16_f32 v2, v2, v161
	global_store_short v[0:1], v2, off offset:64
	v_mul_f32_e32 v2, v35, v76
	v_cvt_pk_bf16_f32 v2, v2, v161
	global_store_short v[0:1], v2, off offset:128
	v_mul_f32_e32 v2, v19, v76
	v_cvt_pk_bf16_f32 v2, v2, v161
	global_store_short v[0:1], v2, off offset:192
	v_mul_f32_e32 v0, v4, v77
	v_cvt_pk_bf16_f32 v4, v0, v161
	v_add_co_u32_e32 v0, vcc, s0, v64
	s_mov_b32 s0, 0x9000
	s_nop 0
	v_addc_co_u32_e32 v1, vcc, 0, v65, vcc
	v_add_co_u32_e32 v2, vcc, s0, v64
	s_mov_b32 s0, 0xa000
	s_nop 0
	v_addc_co_u32_e32 v3, vcc, 0, v65, vcc
	global_store_short v[2:3], v4, off offset:-4096
	v_mul_f32_e32 v4, v52, v77
	v_cvt_pk_bf16_f32 v4, v4, v161
	global_store_short v[0:1], v4, off offset:64
	v_mul_f32_e32 v4, v36, v77
	v_cvt_pk_bf16_f32 v4, v4, v161
	global_store_short v[0:1], v4, off offset:128
	v_mul_f32_e32 v4, v20, v77
	v_cvt_pk_bf16_f32 v4, v4, v161
	global_store_short v[0:1], v4, off offset:192
	v_mul_f32_e32 v0, v5, v78
	v_cvt_pk_bf16_f32 v0, v0, v161
	global_store_short v[2:3], v0, off
	v_mul_f32_e32 v0, v53, v78
	v_cvt_pk_bf16_f32 v0, v0, v161
	global_store_short v[2:3], v0, off offset:64
	v_mul_f32_e32 v0, v37, v78
	v_cvt_pk_bf16_f32 v0, v0, v161
	global_store_short v[2:3], v0, off offset:128
	v_mul_f32_e32 v0, v21, v78
	v_cvt_pk_bf16_f32 v0, v0, v161
	global_store_short v[2:3], v0, off offset:192
	v_mul_f32_e32 v0, v6, v79
	v_cvt_pk_bf16_f32 v4, v0, v161
	v_add_co_u32_e32 v0, vcc, s0, v64
	s_mov_b32 s0, 0xb000
	s_nop 0
	v_addc_co_u32_e32 v1, vcc, 0, v65, vcc
	v_add_co_u32_e32 v2, vcc, s0, v64
	s_mov_b32 s0, 0x10000
	s_nop 0
	v_addc_co_u32_e32 v3, vcc, 0, v65, vcc
	global_store_short v[2:3], v4, off offset:-4096
	v_mul_f32_e32 v4, v54, v79
	v_cvt_pk_bf16_f32 v4, v4, v161
	global_store_short v[0:1], v4, off offset:64
	v_mul_f32_e32 v4, v38, v79
	v_cvt_pk_bf16_f32 v4, v4, v161
	global_store_short v[0:1], v4, off offset:128
	v_mul_f32_e32 v4, v22, v79
	v_cvt_pk_bf16_f32 v4, v4, v161
	global_store_short v[0:1], v4, off offset:192
; __device__ __forceinline__ unsigned cvt_pk_bf16(float lo, float hi) { unsigned r; asm volatile("v_cvt_pk_bf16_f32 %0, %1, %2" : "=v"(r) : "v"(lo), "v"(hi)); return r; }
; __device__ __forceinline__ int crow(int r, int hi) { return (r & 3) + 8 * (r >> 2) + 4 * hi; }
; #define WAIT_BAR() asm volatile("s_waitcnt vmcnt(0) lgkmcnt(0)\n\ts_barrier" ::: "memory")
; __device__ __forceinline__ void attn_unit(const bf16_t* __restrict__ Qb, const bf16_t* __restrict__ Kn, const bf16_t* __restrict__ Vh, const bf16_t* __restrict__ Kr,
;                                           bf16_t* __restrict__ Ob, int seq, char* lds, int wv_) { LAUNDER_IDS;
;     ...
;     bf16_t* Ow = Ob + (long)(wid * QBLK) * LDO;
; #pragma unroll
;     for (int r = 0; r < 16; ++r) { const int orow = crow(r, hi);
; #pragma unroll
;         for (int d0 = 0; d0 < 4; ++d0) Ow[(long)orow * LDO + d0 * 32 + r32] = (bf16_t)(cvt_pk_bf16(o[d0][r] * rli[r], 0.f) & 0xffffu); }
;     WAIT_BAR();
; __device__ __forceinline__ void phase_attention(const Args& a, char* lds, int wv_) { LAUNDER_IDS;
;     ...
;     for (int u = vcu; u < 512; u += G) { const int h = u >> 5, qb = u & 31;
;         att::attn_unit(Q + (size_t)qb * 256 * NQ + h * 192, KV + h * 256, KV + h * 256 + 128, KPE, O + (size_t)qb * 256 * DM + h * 128, SEQ, lds, wv_); }
	v_mul_f32_e32 v0, v7, v80
	v_cvt_pk_bf16_f32 v0, v0, v161
	global_store_short v[2:3], v0, off
	v_mul_f32_e32 v0, v55, v80
	v_cvt_pk_bf16_f32 v0, v0, v161
	global_store_short v[2:3], v0, off offset:64
	v_mul_f32_e32 v0, v39, v80
	v_cvt_pk_bf16_f32 v0, v0, v161
	global_store_short v[2:3], v0, off offset:128
	v_mul_f32_e32 v0, v23, v80
	v_cvt_pk_bf16_f32 v0, v0, v161
	global_store_short v[2:3], v0, off offset:192
	v_mul_f32_e32 v0, v8, v72
	v_cvt_pk_bf16_f32 v4, v0, v161
	v_add_co_u32_e32 v0, vcc, s0, v64
	s_mov_b32 s0, 0x11000
	s_nop 0
	v_addc_co_u32_e32 v1, vcc, 0, v65, vcc
	v_add_co_u32_e32 v2, vcc, s0, v64
	s_mov_b32 s0, 0x12000
	s_nop 0
	v_addc_co_u32_e32 v3, vcc, 0, v65, vcc
	global_store_short v[2:3], v4, off offset:-4096
	v_mul_f32_e32 v4, v56, v72
	v_cvt_pk_bf16_f32 v4, v4, v161
	global_store_short v[0:1], v4, off offset:64
	v_mul_f32_e32 v4, v40, v72
	v_cvt_pk_bf16_f32 v4, v4, v161
	global_store_short v[0:1], v4, off offset:128
	v_mul_f32_e32 v4, v24, v72
	v_cvt_pk_bf16_f32 v4, v4, v161
	global_store_short v[0:1], v4, off offset:192
	v_mul_f32_e32 v0, v9, v81
	v_cvt_pk_bf16_f32 v0, v0, v161
	global_store_short v[2:3], v0, off
	v_mul_f32_e32 v0, v57, v81
	v_cvt_pk_bf16_f32 v0, v0, v161
	global_store_short v[2:3], v0, off offset:64
	v_mul_f32_e32 v0, v41, v81
	v_cvt_pk_bf16_f32 v0, v0, v161
	global_store_short v[2:3], v0, off offset:128
	v_mul_f32_e32 v0, v25, v81
	v_cvt_pk_bf16_f32 v0, v0, v161
	global_store_short v[2:3], v0, off offset:192
	v_mul_f32_e32 v0, v10, v82
	v_cvt_pk_bf16_f32 v4, v0, v161
	v_add_co_u32_e32 v0, vcc, s0, v64
	s_mov_b32 s0, 0x13000
	s_nop 0
	v_addc_co_u32_e32 v1, vcc, 0, v65, vcc
	v_add_co_u32_e32 v2, vcc, s0, v64
	v_rcp_f32_e32 v68, v68
	s_nop 0
	v_addc_co_u32_e32 v3, vcc, 0, v65, vcc
	global_store_short v[2:3], v4, off offset:-4096
	v_mul_f32_e32 v4, v58, v82
	v_cvt_pk_bf16_f32 v4, v4, v161
	global_store_short v[0:1], v4, off offset:64
	v_mul_f32_e32 v4, v42, v82
	v_cvt_pk_bf16_f32 v4, v4, v161
	global_store_short v[0:1], v4, off offset:128
	v_mul_f32_e32 v4, v26, v82
	v_cvt_pk_bf16_f32 v4, v4, v161
	global_store_short v[0:1], v4, off offset:192
	v_mul_f32_e32 v0, v11, v83
	v_cvt_pk_bf16_f32 v0, v0, v161
	global_store_short v[2:3], v0, off
	v_mul_f32_e32 v0, v59, v83
	v_cvt_pk_bf16_f32 v0, v0, v161
	global_store_short v[2:3], v0, off offset:64
	v_mul_f32_e32 v0, v43, v83
	v_cvt_pk_bf16_f32 v0, v0, v161
	global_store_short v[2:3], v0, off offset:128
	v_mul_f32_e32 v0, v27, v83
	v_cvt_pk_bf16_f32 v0, v0, v161
	global_store_short v[2:3], v0, off offset:192
	v_mul_f32_e32 v0, v12, v68
	s_mov_b32 s0, 0x18000
	v_cvt_pk_bf16_f32 v4, v0, v161
	v_add_co_u32_e32 v0, vcc, s0, v64
	s_mov_b32 s0, 0x19000
	s_nop 0
	v_addc_co_u32_e32 v1, vcc, 0, v65, vcc
	v_add_co_u32_e32 v2, vcc, s0, v64
	v_rcp_f32_e32 v69, v69
	s_nop 0
	v_addc_co_u32_e32 v3, vcc, 0, v65, vcc
	global_store_short v[2:3], v4, off offset:-4096
	v_mul_f32_e32 v4, v60, v68
	v_cvt_pk_bf16_f32 v4, v4, v161
	global_store_short v[0:1], v4, off offset:64
	v_mul_f32_e32 v4, v44, v68
	v_cvt_pk_bf16_f32 v4, v4, v161
	global_store_short v[0:1], v4, off offset:128
	v_mul_f32_e32 v4, v28, v68
	v_cvt_pk_bf16_f32 v4, v4, v161
	global_store_short v[0:1], v4, off offset:192
	v_mul_f32_e32 v0, v13, v69
	v_cvt_pk_bf16_f32 v0, v0, v161
	global_store_short v[2:3], v0, off
	v_mul_f32_e32 v0, v61, v69
	v_cvt_pk_bf16_f32 v0, v0, v161
	v_rcp_f32_e32 v70, v70
	global_store_short v[2:3], v0, off offset:64
	v_mul_f32_e32 v0, v45, v69
	v_cvt_pk_bf16_f32 v0, v0, v161
	global_store_short v[2:3], v0, off offset:128
	v_mul_f32_e32 v0, v29, v69
	v_cvt_pk_bf16_f32 v0, v0, v161
	global_store_short v[2:3], v0, off offset:192
	v_mul_f32_e32 v0, v14, v70
	s_mov_b32 s0, 0x1a000
	v_cvt_pk_bf16_f32 v4, v0, v161
	v_add_co_u32_e32 v0, vcc, s0, v64
	s_mov_b32 s0, 0x1b000
	s_nop 0
	v_addc_co_u32_e32 v1, vcc, 0, v65, vcc
	v_add_co_u32_e32 v2, vcc, s0, v64
	v_rcp_f32_e32 v71, v71
	s_nop 0
	v_addc_co_u32_e32 v3, vcc, 0, v65, vcc
	global_store_short v[2:3], v4, off offset:-4096
	v_mul_f32_e32 v4, v62, v70
	v_cvt_pk_bf16_f32 v4, v4, v161
	global_store_short v[0:1], v4, off offset:64
	v_mul_f32_e32 v4, v46, v70
	v_cvt_pk_bf16_f32 v4, v4, v161
	global_store_short v[0:1], v4, off offset:128
	v_mul_f32_e32 v4, v30, v70
	v_cvt_pk_bf16_f32 v4, v4, v161
	global_store_short v[0:1], v4, off offset:192
	v_mul_f32_e32 v0, v15, v71
	v_cvt_pk_bf16_f32 v0, v0, v161
	global_store_short v[2:3], v0, off
	v_mul_f32_e32 v0, v63, v71
	v_cvt_pk_bf16_f32 v0, v0, v161
	global_store_short v[2:3], v0, off offset:64
	v_mul_f32_e32 v0, v47, v71
	v_cvt_pk_bf16_f32 v0, v0, v161
	global_store_short v[2:3], v0, off offset:128
	v_mul_f32_e32 v0, v31, v71
	v_cvt_pk_bf16_f32 v0, v0, v161
	global_store_short v[2:3], v0, off offset:192
	s_waitcnt lgkmcnt(0)
	s_barrier
	s_add_i32 s2, s2, s76
	s_cmpk_lt_i32 s2, 0x200
	s_cbranch_scc0 .LBB0_200
